# HG lower-bound table staged once per workgroup; weight-conversion LDS transposing reads hoisted
# speedup vs baseline: 1.0055x; 1.0055x over previous
; #define LAS __attribute__((address_space(3)))
; __device__ __forceinline__ void tr_item(const float* W, int K, int N, bf16_t* WT, int rowbase, int k0, int n0, LAS float* scr, int lane) {
;     const int n = n0 + (lane & 31);
;     float tv[32];
; #pragma unroll
;     for (int i = 0; i < 32; ++i) { const int kk = 2 * i + (lane >> 5); tv[i] = 0.f; if (n < N) tv[i] = __builtin_nontemporal_load(W + (size_t)(k0 + kk) * N + n); }
.LBB0_22:
	s_andn2_b64 vcc, exec, s[4:5]
	s_cbranch_vccnz .LBB0_24
	v_readlane_b32 s2, v253, 36
	s_nop 1
	v_mov_b32_e32 v0, s2
	ds_read_b64 v[16:17], v0
	s_waitcnt lgkmcnt(0)
	v_readfirstlane_b32 s4, v16
	v_readfirstlane_b32 s5, v17
	s_add_u32 s12, s4, s14
	s_addc_u32 s13, s5, 0
	s_and_b32 s4, s16, 0x3e0
	s_and_b32 s5, s17, 0x7fc0
	s_add_i32 s72, s5, 0xffffadc0
	v_or_b32_e32 v0, s4, v2
	v_or_b32_e32 v16, s72, v3
	v_lshlrev_b32_e32 v0, 2, v0
	v_lshl_add_u64 v[18:19], s[12:13], 0, v[0:1]
	v_or_b32_e32 v0, 2, v16
	v_lshlrev_b64 v[34:35], 12, v[0:1]
	v_or_b32_e32 v0, 4, v16
	v_lshlrev_b64 v[36:37], 12, v[0:1]
	v_or_b32_e32 v0, 6, v16
	v_lshlrev_b64 v[38:39], 12, v[0:1]
	v_or_b32_e32 v0, 8, v16
	v_lshlrev_b64 v[40:41], 12, v[0:1]
	v_or_b32_e32 v0, 10, v16
	v_mov_b32_e32 v17, v1
	v_lshlrev_b64 v[42:43], 12, v[0:1]
	v_or_b32_e32 v0, 12, v16
	v_lshlrev_b64 v[32:33], 12, v[16:17]
	v_lshlrev_b64 v[44:45], 12, v[0:1]
	v_or_b32_e32 v0, 14, v16
	v_lshl_add_u64 v[32:33], v[18:19], 0, v[32:33]
	v_lshlrev_b64 v[46:47], 12, v[0:1]
	v_or_b32_e32 v0, 16, v16
	v_lshl_add_u64 v[34:35], v[18:19], 0, v[34:35]
	v_lshl_add_u64 v[36:37], v[18:19], 0, v[36:37]
	v_lshl_add_u64 v[38:39], v[18:19], 0, v[38:39]
	v_lshl_add_u64 v[40:41], v[18:19], 0, v[40:41]
	v_lshl_add_u64 v[42:43], v[18:19], 0, v[42:43]
	v_lshl_add_u64 v[44:45], v[18:19], 0, v[44:45]
	v_lshl_add_u64 v[46:47], v[18:19], 0, v[46:47]
	global_load_dword v48, v[32:33], off nt
	global_load_dword v49, v[34:35], off nt
	global_load_dword v50, v[36:37], off nt
	global_load_dword v51, v[38:39], off nt
	global_load_dword v52, v[40:41], off nt
	global_load_dword v53, v[42:43], off nt
	global_load_dword v54, v[44:45], off nt
	global_load_dword v55, v[46:47], off nt
	v_lshlrev_b64 v[32:33], 12, v[0:1]
	v_or_b32_e32 v0, 18, v16
	v_lshlrev_b64 v[34:35], 12, v[0:1]
	v_or_b32_e32 v0, 20, v16
	v_lshlrev_b64 v[36:37], 12, v[0:1]
	v_or_b32_e32 v0, 22, v16
	v_lshlrev_b64 v[38:39], 12, v[0:1]
	v_or_b32_e32 v0, 24, v16
	v_lshlrev_b64 v[40:41], 12, v[0:1]
	v_or_b32_e32 v0, 26, v16
	v_lshlrev_b64 v[42:43], 12, v[0:1]
	v_or_b32_e32 v0, 28, v16
	v_lshlrev_b64 v[44:45], 12, v[0:1]
	v_or_b32_e32 v0, 30, v16
	v_lshl_add_u64 v[32:33], v[18:19], 0, v[32:33]
	v_lshlrev_b64 v[46:47], 12, v[0:1]
	v_or_b32_e32 v0, 32, v16
	v_lshl_add_u64 v[34:35], v[18:19], 0, v[34:35]
	v_lshl_add_u64 v[36:37], v[18:19], 0, v[36:37]
	v_lshl_add_u64 v[38:39], v[18:19], 0, v[38:39]
	v_lshl_add_u64 v[40:41], v[18:19], 0, v[40:41]
	v_lshl_add_u64 v[42:43], v[18:19], 0, v[42:43]
	v_lshl_add_u64 v[44:45], v[18:19], 0, v[44:45]
	v_lshl_add_u64 v[46:47], v[18:19], 0, v[46:47]
	global_load_dword v56, v[32:33], off nt
	global_load_dword v57, v[34:35], off nt
	global_load_dword v58, v[36:37], off nt
	global_load_dword v59, v[38:39], off nt
	global_load_dword v60, v[40:41], off nt
	global_load_dword v61, v[42:43], off nt
	global_load_dword v62, v[44:45], off nt
	global_load_dword v63, v[46:47], off nt
	v_lshlrev_b64 v[32:33], 12, v[0:1]
	v_or_b32_e32 v0, 34, v16
	v_lshlrev_b64 v[34:35], 12, v[0:1]
	v_or_b32_e32 v0, 36, v16
	v_lshlrev_b64 v[36:37], 12, v[0:1]
	v_or_b32_e32 v0, 38, v16
	v_lshlrev_b64 v[38:39], 12, v[0:1]
	v_or_b32_e32 v0, 40, v16
	v_lshlrev_b64 v[40:41], 12, v[0:1]
	v_or_b32_e32 v0, 42, v16
	v_lshlrev_b64 v[42:43], 12, v[0:1]
	v_or_b32_e32 v0, 44, v16
	v_lshlrev_b64 v[44:45], 12, v[0:1]
	v_or_b32_e32 v0, 46, v16
	v_lshlrev_b64 v[46:47], 12, v[0:1]
	v_lshl_add_u64 v[32:33], v[18:19], 0, v[32:33]
	v_lshl_add_u64 v[46:47], v[18:19], 0, v[46:47]
	v_or_b32_e32 v0, 48, v16
	v_lshl_add_u64 v[34:35], v[18:19], 0, v[34:35]
	v_lshl_add_u64 v[36:37], v[18:19], 0, v[36:37]
	v_lshl_add_u64 v[38:39], v[18:19], 0, v[38:39]
	v_lshl_add_u64 v[40:41], v[18:19], 0, v[40:41]
	v_lshl_add_u64 v[42:43], v[18:19], 0, v[42:43]
	v_lshl_add_u64 v[44:45], v[18:19], 0, v[44:45]
	global_load_dword v64, v[32:33], off nt
	global_load_dword v65, v[34:35], off nt
	global_load_dword v66, v[36:37], off nt
	global_load_dword v67, v[38:39], off nt
	global_load_dword v68, v[40:41], off nt
	global_load_dword v69, v[42:43], off nt
	global_load_dword v70, v[44:45], off nt
	s_nop 0
	global_load_dword v46, v[46:47], off nt
	v_lshlrev_b64 v[32:33], 12, v[0:1]
	v_or_b32_e32 v0, 50, v16
	v_lshlrev_b64 v[34:35], 12, v[0:1]
	v_or_b32_e32 v0, 52, v16
	v_lshlrev_b64 v[36:37], 12, v[0:1]
	v_or_b32_e32 v0, 54, v16
	v_lshlrev_b64 v[38:39], 12, v[0:1]
	v_or_b32_e32 v0, 56, v16
	v_lshlrev_b64 v[40:41], 12, v[0:1]
	v_or_b32_e32 v0, 58, v16
	v_lshlrev_b64 v[42:43], 12, v[0:1]
	v_or_b32_e32 v0, 60, v16
	v_lshlrev_b64 v[44:45], 12, v[0:1]
	v_or_b32_e32 v0, 62, v16
	v_lshlrev_b64 v[16:17], 12, v[0:1]
	v_lshl_add_u64 v[32:33], v[18:19], 0, v[32:33]
	v_lshl_add_u64 v[34:35], v[18:19], 0, v[34:35]
	v_lshl_add_u64 v[16:17], v[18:19], 0, v[16:17]
	v_lshl_add_u64 v[36:37], v[18:19], 0, v[36:37]
	v_lshl_add_u64 v[38:39], v[18:19], 0, v[38:39]
	v_lshl_add_u64 v[40:41], v[18:19], 0, v[40:41]
	v_lshl_add_u64 v[42:43], v[18:19], 0, v[42:43]
	v_lshl_add_u64 v[44:45], v[18:19], 0, v[44:45]
	global_load_dword v0, v[32:33], off nt
	global_load_dword v18, v[34:35], off nt
	global_load_dword v19, v[36:37], off nt
	s_nop 0
	global_load_dword v32, v[38:39], off nt
	global_load_dword v33, v[40:41], off nt
	global_load_dword v34, v[42:43], off nt
	global_load_dword v35, v[44:45], off nt
	s_nop 0
	global_load_dword v16, v[16:17], off nt
	s_waitcnt vmcnt(30)
; #define LAS __attribute__((address_space(3)))
; __device__ __forceinline__ unsigned pk2(float lo, float hi) { return pg8::cvt_pk_bf16(lo, hi); }
; #define LDS_WAIT() asm volatile("s_waitcnt lgkmcnt(0)" ::: "memory")
; __device__ __forceinline__ void tr_item(const float* W, int K, int N, bf16_t* WT, int rowbase, int k0, int n0, LAS float* scr, int lane) {
;     ...
;     for (int i = 0; i < 32; ++i) { const int kk = 2 * i + (lane >> 5); scr[kk * 33 + (lane & 31)] = tv[i]; }
;     LDS_WAIT();
;     const int c = lane & 7;
; #pragma unroll
;     for (int j = 0; j < 4; ++j) {
;         const int nn = (lane >> 3) + 8 * j; const LAS float* s = scr + (8 * c) * 33 + nn;
;         u32x4 o; o.x = pk2(s[0 * 33], s[1 * 33]); o.y = pk2(s[2 * 33], s[3 * 33]); o.z = pk2(s[4 * 33], s[5 * 33]); o.w = pk2(s[6 * 33], s[7 * 33]);
;         *(u32x4*)(WT + (size_t)(rowbase + nn) * K + k0 + 8 * c) = o;
;     }
;     LDS_WAIT();
	ds_write2_b32 v7, v48, v49 offset1:66
	s_waitcnt vmcnt(28)
	ds_write2_b32 v7, v50, v51 offset0:132 offset1:198
	s_waitcnt vmcnt(26)
	ds_write2_b32 v25, v52, v53 offset0:8 offset1:74
	s_waitcnt vmcnt(24)
	ds_write2_b32 v25, v54, v55 offset0:140 offset1:206
	s_waitcnt vmcnt(22)
	ds_write2_b32 v26, v56, v57 offset0:16 offset1:82
	s_waitcnt vmcnt(20)
	ds_write2_b32 v26, v58, v59 offset0:148 offset1:214
	s_waitcnt vmcnt(18)
	ds_write2_b32 v27, v60, v61 offset0:24 offset1:90
	s_waitcnt vmcnt(16)
	ds_write2_b32 v27, v62, v63 offset0:156 offset1:222
	s_waitcnt vmcnt(14)
	ds_write2_b32 v28, v64, v65 offset0:32 offset1:98
	s_waitcnt vmcnt(12)
	ds_write2_b32 v28, v66, v67 offset0:164 offset1:230
	s_waitcnt vmcnt(10)
	ds_write2_b32 v29, v68, v69 offset0:40 offset1:106
	s_waitcnt vmcnt(8)
	ds_write2_b32 v29, v70, v46 offset0:172 offset1:238
	s_waitcnt vmcnt(6)
	ds_write2_b32 v30, v0, v18 offset0:48 offset1:114
	s_waitcnt vmcnt(4)
	ds_write2_b32 v30, v19, v32 offset0:180 offset1:246
	s_waitcnt vmcnt(2)
	ds_write2_b32 v31, v33, v34 offset0:56 offset1:122
	s_waitcnt vmcnt(0)
	ds_write2_b32 v31, v35, v16 offset0:188 offset1:254
	s_waitcnt lgkmcnt(0)
	ds_read2_b32 v[80:81], v21 offset1:33
	ds_read2_b32 v[82:83], v21 offset0:66 offset1:99
	ds_read2_b32 v[84:85], v21 offset0:132 offset1:165
	ds_read2_b32 v[86:87], v21 offset0:198 offset1:231
	ds_read2_b32 v[88:89], v21 offset0:8 offset1:41
	ds_read2_b32 v[90:91], v21 offset0:74 offset1:107
	ds_read2_b32 v[92:93], v21 offset0:140 offset1:173
	ds_read2_b32 v[94:95], v21 offset0:206 offset1:239
	ds_read2_b32 v[96:97], v21 offset0:16 offset1:49
	ds_read2_b32 v[98:99], v21 offset0:82 offset1:115
	ds_read2_b32 v[100:101], v21 offset0:148 offset1:181
	ds_read2_b32 v[102:103], v21 offset0:214 offset1:247
	ds_read2_b32 v[104:105], v21 offset0:24 offset1:57
	ds_read2_b32 v[106:107], v21 offset0:90 offset1:123
	ds_read2_b32 v[108:109], v21 offset0:156 offset1:189
	s_waitcnt lgkmcnt(14)
	ds_read2_b32 v[110:111], v21 offset0:222 offset1:255
	v_cvt_pk_bf16_f32 v16, v80, v81
	v_or_b32_e32 v0, s4, v20
	s_waitcnt lgkmcnt(14)
	v_cvt_pk_bf16_f32 v17, v82, v83
	v_lshl_add_u64 v[34:35], s[72:73], 1, v[8:9]
	v_lshlrev_b32_e32 v0, 11, v0
	s_waitcnt lgkmcnt(13)
	v_cvt_pk_bf16_f32 v18, v84, v85
	s_waitcnt lgkmcnt(12)
	v_cvt_pk_bf16_f32 v19, v86, v87
	v_lshl_add_u64 v[36:37], v[34:35], 0, v[0:1]
	global_store_dwordx4 v[36:37], v[16:19], off
	v_or_b32_e32 v0, s4, v22
	v_lshlrev_b32_e32 v0, 11, v0
	s_waitcnt lgkmcnt(11)
	v_cvt_pk_bf16_f32 v16, v88, v89
	s_waitcnt lgkmcnt(10)
	v_cvt_pk_bf16_f32 v17, v90, v91
	s_waitcnt lgkmcnt(9)
	v_cvt_pk_bf16_f32 v18, v92, v93
	s_waitcnt lgkmcnt(8)
	v_cvt_pk_bf16_f32 v19, v94, v95
	v_lshl_add_u64 v[36:37], v[34:35], 0, v[0:1]
	global_store_dwordx4 v[36:37], v[16:19], off
	v_or_b32_e32 v0, s4, v23
	v_lshlrev_b32_e32 v0, 11, v0
	s_waitcnt lgkmcnt(7)
	v_cvt_pk_bf16_f32 v16, v96, v97
	s_waitcnt lgkmcnt(6)
	v_cvt_pk_bf16_f32 v17, v98, v99
	s_waitcnt lgkmcnt(5)
	v_cvt_pk_bf16_f32 v18, v100, v101
	s_waitcnt lgkmcnt(4)
	v_cvt_pk_bf16_f32 v19, v102, v103
	v_lshl_add_u64 v[36:37], v[34:35], 0, v[0:1]
	global_store_dwordx4 v[36:37], v[16:19], off
	v_or_b32_e32 v0, s4, v24
	v_lshlrev_b32_e32 v0, 11, v0
	s_waitcnt lgkmcnt(3)
	v_cvt_pk_bf16_f32 v16, v104, v105
	s_waitcnt lgkmcnt(2)
	v_cvt_pk_bf16_f32 v17, v106, v107
	s_waitcnt lgkmcnt(1)
	v_cvt_pk_bf16_f32 v18, v108, v109
	s_waitcnt lgkmcnt(0)
	v_cvt_pk_bf16_f32 v19, v110, v111
	v_lshl_add_u64 v[32:33], v[34:35], 0, v[0:1]
	global_store_dwordx4 v[32:33], v[16:19], off
	s_waitcnt lgkmcnt(0)

; #define LAS __attribute__((address_space(3)))
; __device__ __forceinline__ unsigned pk2(float lo, float hi) { return pg8::cvt_pk_bf16(lo, hi); }
; #define LDS_WAIT() asm volatile("s_waitcnt lgkmcnt(0)" ::: "memory")
; __device__ __forceinline__ void tr_item(const float* W, int K, int N, bf16_t* WT, int rowbase, int k0, int n0, LAS float* scr, int lane) {
;     ...
;     for (int i = 0; i < 32; ++i) { const int kk = 2 * i + (lane >> 5); scr[kk * 33 + (lane & 31)] = tv[i]; }
;     LDS_WAIT();
;     const int c = lane & 7;
; #pragma unroll
;     for (int j = 0; j < 4; ++j) {
;         const int nn = (lane >> 3) + 8 * j; const LAS float* s = scr + (8 * c) * 33 + nn;
;         u32x4 o; o.x = pk2(s[0 * 33], s[1 * 33]); o.y = pk2(s[2 * 33], s[3 * 33]); o.z = pk2(s[4 * 33], s[5 * 33]); o.w = pk2(s[6 * 33], s[7 * 33]);
;         *(u32x4*)(WT + (size_t)(rowbase + nn) * K + k0 + 8 * c) = o;
;     }
;     LDS_WAIT();
.LBB0_62:
	s_waitcnt vmcnt(0)
	ds_write2_b32 v7, v17, v32 offset1:66
	ds_write2_b32 v7, v34, v33 offset0:132 offset1:198
	ds_write2_b32 v25, v36, v35 offset0:8 offset1:74
	ds_write2_b32 v25, v38, v37 offset0:140 offset1:206
	ds_write2_b32 v26, v40, v39 offset0:16 offset1:82
	ds_write2_b32 v26, v42, v41 offset0:148 offset1:214
	ds_write2_b32 v27, v44, v43 offset0:24 offset1:90
	ds_write2_b32 v27, v46, v45 offset0:156 offset1:222
	ds_write2_b32 v28, v48, v47 offset0:32 offset1:98
	ds_write2_b32 v28, v50, v49 offset0:164 offset1:230
	ds_write2_b32 v29, v52, v51 offset0:40 offset1:106
	ds_write2_b32 v29, v54, v53 offset0:172 offset1:238
	ds_write2_b32 v30, v56, v55 offset0:48 offset1:114
	ds_write2_b32 v30, v58, v57 offset0:180 offset1:246
	ds_write2_b32 v31, v60, v59 offset0:56 offset1:122
	ds_write2_b32 v31, v62, v61 offset0:188 offset1:254
	s_waitcnt lgkmcnt(0)
	ds_read2_b32 v[80:81], v21 offset1:33
	ds_read2_b32 v[82:83], v21 offset0:66 offset1:99
	ds_read2_b32 v[84:85], v21 offset0:132 offset1:165
	ds_read2_b32 v[86:87], v21 offset0:198 offset1:231
	ds_read2_b32 v[88:89], v21 offset0:8 offset1:41
	ds_read2_b32 v[90:91], v21 offset0:74 offset1:107
	ds_read2_b32 v[92:93], v21 offset0:140 offset1:173
	ds_read2_b32 v[94:95], v21 offset0:206 offset1:239
	ds_read2_b32 v[96:97], v21 offset0:16 offset1:49
	ds_read2_b32 v[98:99], v21 offset0:82 offset1:115
	ds_read2_b32 v[100:101], v21 offset0:148 offset1:181
	ds_read2_b32 v[102:103], v21 offset0:214 offset1:247
	ds_read2_b32 v[104:105], v21 offset0:24 offset1:57
	ds_read2_b32 v[106:107], v21 offset0:90 offset1:123
	ds_read2_b32 v[108:109], v21 offset0:156 offset1:189
	s_waitcnt lgkmcnt(14)
	ds_read2_b32 v[110:111], v21 offset0:222 offset1:255
	v_cvt_pk_bf16_f32 v16, v80, v81
	s_waitcnt lgkmcnt(14)
	v_cvt_pk_bf16_f32 v17, v82, v83
	s_waitcnt lgkmcnt(13)
	v_cvt_pk_bf16_f32 v18, v84, v85
	s_mov_b32 s11, s73
	s_waitcnt lgkmcnt(12)
	v_cvt_pk_bf16_f32 v19, v86, v87
	v_lshl_add_u64 v[32:33], s[10:11], 1, v[14:15]
	s_mov_b32 s4, 0x2c0000
	v_add_co_u32_e32 v36, vcc, s4, v32
	s_nop 0
	v_addc_co_u32_e32 v37, vcc, 0, v33, vcc
	global_store_dwordx4 v[36:37], v[16:19], off
	s_mov_b32 s4, 0x2c4000
	v_add_co_u32_e32 v36, vcc, s4, v32
	s_waitcnt lgkmcnt(11)
	v_cvt_pk_bf16_f32 v16, v88, v89
	s_waitcnt lgkmcnt(10)
	v_cvt_pk_bf16_f32 v17, v90, v91
	s_waitcnt lgkmcnt(9)
	v_cvt_pk_bf16_f32 v18, v92, v93
	s_waitcnt lgkmcnt(8)
	v_cvt_pk_bf16_f32 v19, v94, v95
	v_addc_co_u32_e32 v37, vcc, 0, v33, vcc
	global_store_dwordx4 v[36:37], v[16:19], off
	s_mov_b32 s4, 0x2c8000
	v_add_co_u32_e32 v36, vcc, s4, v32
	s_waitcnt lgkmcnt(7)
	v_cvt_pk_bf16_f32 v16, v96, v97
	s_waitcnt lgkmcnt(6)
	v_cvt_pk_bf16_f32 v17, v98, v99
	s_waitcnt lgkmcnt(5)
	v_cvt_pk_bf16_f32 v18, v100, v101
	s_waitcnt lgkmcnt(4)
	v_cvt_pk_bf16_f32 v19, v102, v103
	v_addc_co_u32_e32 v37, vcc, 0, v33, vcc
	global_store_dwordx4 v[36:37], v[16:19], off
	v_add_co_u32_e32 v32, vcc, 0x2cc000, v32
	s_waitcnt lgkmcnt(3)
	v_cvt_pk_bf16_f32 v16, v104, v105
	s_waitcnt lgkmcnt(2)
	v_cvt_pk_bf16_f32 v17, v106, v107
	v_addc_co_u32_e32 v33, vcc, 0, v33, vcc
	s_waitcnt lgkmcnt(1)
	v_cvt_pk_bf16_f32 v18, v108, v109
	s_waitcnt lgkmcnt(0)
	v_cvt_pk_bf16_f32 v19, v110, v111
	global_store_dwordx4 v[32:33], v[16:19], off
	s_waitcnt lgkmcnt(0)

; #define LAS __attribute__((address_space(3)))
; __device__ __forceinline__ unsigned pk2(float lo, float hi) { return pg8::cvt_pk_bf16(lo, hi); }
; #define LDS_WAIT() asm volatile("s_waitcnt lgkmcnt(0)" ::: "memory")
; __device__ __forceinline__ void tr_item(const float* W, int K, int N, bf16_t* WT, int rowbase, int k0, int n0, LAS float* scr, int lane) {
;     ...
;     for (int i = 0; i < 32; ++i) { const int kk = 2 * i + (lane >> 5); scr[kk * 33 + (lane & 31)] = tv[i]; }
;     LDS_WAIT();
;     const int c = lane & 7;
; #pragma unroll
;     for (int j = 0; j < 4; ++j) {
;         const int nn = (lane >> 3) + 8 * j; const LAS float* s = scr + (8 * c) * 33 + nn;
;         u32x4 o; o.x = pk2(s[0 * 33], s[1 * 33]); o.y = pk2(s[2 * 33], s[3 * 33]); o.z = pk2(s[4 * 33], s[5 * 33]); o.w = pk2(s[6 * 33], s[7 * 33]);
;         *(u32x4*)(WT + (size_t)(rowbase + nn) * K + k0 + 8 * c) = o;
;     }
;     LDS_WAIT();
.LBB0_129:
	s_or_b64 exec, exec, s[12:13]
	s_waitcnt vmcnt(0)
	ds_write2_b32 v7, v18, v19 offset1:66
	ds_write2_b32 v7, v33, v32 offset0:132 offset1:198
	ds_write2_b32 v25, v35, v34 offset0:8 offset1:74
	ds_write2_b32 v25, v37, v36 offset0:140 offset1:206
	ds_write2_b32 v26, v39, v38 offset0:16 offset1:82
	ds_write2_b32 v26, v41, v40 offset0:148 offset1:214
	ds_write2_b32 v27, v43, v42 offset0:24 offset1:90
	ds_write2_b32 v27, v45, v44 offset0:156 offset1:222
	ds_write2_b32 v28, v47, v46 offset0:32 offset1:98
	ds_write2_b32 v28, v49, v48 offset0:164 offset1:230
	ds_write2_b32 v29, v51, v50 offset0:40 offset1:106
	ds_write2_b32 v29, v53, v52 offset0:172 offset1:238
	ds_write2_b32 v30, v55, v54 offset0:48 offset1:114
	ds_write2_b32 v30, v57, v56 offset0:180 offset1:246
	ds_write2_b32 v31, v59, v58 offset0:56 offset1:122
	ds_write2_b32 v31, v61, v60 offset0:188 offset1:254
	s_and_b32 s4, 0xffff, s20
	s_add_i32 s5, s11, 0x80
	s_waitcnt lgkmcnt(0)
	s_cmp_lt_u32 s4, 44
	ds_read2_b32 v[80:81], v21 offset1:33
	ds_read2_b32 v[82:83], v21 offset0:66 offset1:99
	ds_read2_b32 v[84:85], v21 offset0:132 offset1:165
	ds_read2_b32 v[86:87], v21 offset0:198 offset1:231
	ds_read2_b32 v[88:89], v21 offset0:8 offset1:41
	ds_read2_b32 v[90:91], v21 offset0:74 offset1:107
	ds_read2_b32 v[92:93], v21 offset0:140 offset1:173
	ds_read2_b32 v[94:95], v21 offset0:206 offset1:239
	ds_read2_b32 v[96:97], v21 offset0:16 offset1:49
	ds_read2_b32 v[98:99], v21 offset0:82 offset1:115
	ds_read2_b32 v[100:101], v21 offset0:148 offset1:181
	ds_read2_b32 v[102:103], v21 offset0:214 offset1:247
	ds_read2_b32 v[104:105], v21 offset0:24 offset1:57
	ds_read2_b32 v[106:107], v21 offset0:90 offset1:123
	ds_read2_b32 v[108:109], v21 offset0:156 offset1:189
	s_cselect_b32 s4, s11, s5
	s_and_b32 s5, 0xffff, s21
	s_waitcnt lgkmcnt(14)
	ds_read2_b32 v[110:111], v21 offset0:222 offset1:255
	v_cvt_pk_bf16_f32 v16, v80, v81
	s_lshl_b32 s72, s5, 1
	v_or_b32_e32 v0, s4, v20
	s_waitcnt lgkmcnt(14)
	v_cvt_pk_bf16_f32 v17, v82, v83
	v_lshl_add_u64 v[34:35], v[12:13], 0, s[72:73]
	v_lshlrev_b32_e32 v0, 11, v0
	s_waitcnt lgkmcnt(13)
	v_cvt_pk_bf16_f32 v18, v84, v85
	s_waitcnt lgkmcnt(12)
	v_cvt_pk_bf16_f32 v19, v86, v87
	v_lshl_add_u64 v[36:37], v[34:35], 0, v[0:1]
	global_store_dwordx4 v[36:37], v[16:19], off
	v_or_b32_e32 v0, s4, v22
	v_lshlrev_b32_e32 v0, 11, v0
	s_waitcnt lgkmcnt(11)
	v_cvt_pk_bf16_f32 v16, v88, v89
	s_waitcnt lgkmcnt(10)
	v_cvt_pk_bf16_f32 v17, v90, v91
	s_waitcnt lgkmcnt(9)
	v_cvt_pk_bf16_f32 v18, v92, v93
	s_waitcnt lgkmcnt(8)
	v_cvt_pk_bf16_f32 v19, v94, v95
	v_lshl_add_u64 v[36:37], v[34:35], 0, v[0:1]
	global_store_dwordx4 v[36:37], v[16:19], off
	v_or_b32_e32 v0, s4, v23
	v_lshlrev_b32_e32 v0, 11, v0
	s_waitcnt lgkmcnt(7)
	v_cvt_pk_bf16_f32 v16, v96, v97
	s_waitcnt lgkmcnt(6)
	v_cvt_pk_bf16_f32 v17, v98, v99
	s_waitcnt lgkmcnt(5)
	v_cvt_pk_bf16_f32 v18, v100, v101
	s_waitcnt lgkmcnt(4)
	v_cvt_pk_bf16_f32 v19, v102, v103
	v_lshl_add_u64 v[36:37], v[34:35], 0, v[0:1]
	global_store_dwordx4 v[36:37], v[16:19], off
	v_or_b32_e32 v0, s4, v24
	v_lshlrev_b32_e32 v0, 11, v0
	s_waitcnt lgkmcnt(3)
	v_cvt_pk_bf16_f32 v16, v104, v105
	s_waitcnt lgkmcnt(2)
	v_cvt_pk_bf16_f32 v17, v106, v107
	s_waitcnt lgkmcnt(1)
	v_cvt_pk_bf16_f32 v18, v108, v109
	s_waitcnt lgkmcnt(0)
	v_cvt_pk_bf16_f32 v19, v110, v111
	v_lshl_add_u64 v[32:33], v[34:35], 0, v[0:1]
	global_store_dwordx4 v[32:33], v[16:19], off
	s_waitcnt lgkmcnt(0)

; #define LAS __attribute__((address_space(3)))
;     __device__ __forceinline__ const float* in(int i) const { return (const float*)(const __attribute__((address_space(1))) float*)ld(i); }
;     __device__ __forceinline__ unsigned char* ws() const { return (unsigned char*)(__attribute__((address_space(1))) unsigned char*)ld(35); }
; __device__ __forceinline__ void tr_item(const float* W, int K, int N, bf16_t* WT, int rowbase, int k0, int n0, LAS float* scr, int lane) {
;     const int n = n0 + (lane & 31);
;     float tv[32];
; #pragma unroll
;     for (int i = 0; i < 32; ++i) { const int kk = 2 * i + (lane >> 5); tv[i] = 0.f; if (n < N) tv[i] = __builtin_nontemporal_load(W + (size_t)(k0 + kk) * N + n); }
; __device__ __forceinline__ void phase_convert(const Params& p, int l, LAS unsigned char* lds, int gw, int ngw, int wave, int lane) {
;     ...
;         if (r < 2 * I_DN) {
;             const int which = r / I_DN; r -= which * I_DN;
;             const int kb = r / 32, nb = r % 32;
;             tr_item(p.in(which ? 32 : 4) + (size_t)l * FF * D, FF, D, (bf16_t*)(ws + (which ? WS_WDN2 : WS_WDN1)), 32 * nb, 64 * kb, 32 * nb, scr, lane);
;             continue;
.LBB0_131:
	s_andn2_b64 vcc, exec, s[4:5]
	s_cbranch_vccnz .LBB0_133
	s_add_i32 s11, s19, 0xffffea00
	s_add_i32 s20, s19, 0xffffe480
	s_cmpk_lt_u32 s11, 0x580
	s_cselect_b64 s[4:5], -1, 0
	s_and_b64 s[12:13], s[4:5], exec
	s_cselect_b32 s12, s11, s20
	s_cselect_b32 s11, 32, 0x100
	s_add_i32 s11, s11, 0
	s_add_i32 s11, s11, 0x23800
	v_mov_b32_e32 v0, s11
	ds_read_b64 v[16:17], v0
	s_mov_b32 s2, 0x8000
	s_waitcnt lgkmcnt(0)
	v_readfirstlane_b32 s11, v16
	v_readfirstlane_b32 s13, v17
	s_add_u32 s20, s11, s15
	s_addc_u32 s21, s13, 0
	s_and_b64 s[4:5], s[4:5], exec
	s_mov_b32 s4, 0x4b00000
	s_cselect_b32 s4, s4, 0x5b80000
	s_add_u32 s5, s0, s4
	s_addc_u32 s11, s1, 0
	s_lshl_b32 s4, s12, 5
	s_and_b32 s4, s4, 0x3e0
	s_lshl_b32 s12, s12, 1
	s_and_b32 s12, s12, 0xfc0
	v_or_b32_e32 v0, s4, v2
	v_or_b32_e32 v18, s12, v3
	v_lshlrev_b32_e32 v0, 2, v0
	v_lshl_add_u64 v[16:17], s[20:21], 0, v[0:1]
	v_lshlrev_b32_e32 v0, 12, v18
	v_lshl_add_u64 v[16:17], v[16:17], 0, v[0:1]
	s_movk_i32 s13, 0x2000
	v_add_co_u32_e32 v18, vcc, s13, v16
	s_movk_i32 s13, 0x4000
	s_nop 0
	v_addc_co_u32_e32 v19, vcc, 0, v17, vcc
	v_add_co_u32_e32 v32, vcc, s13, v16
	s_mov_b32 s13, 0xa000
	s_nop 0
	v_addc_co_u32_e32 v33, vcc, 0, v17, vcc
	v_add_co_u32_e32 v34, vcc, s54, v16
	s_lshl_b32 s12, s12, 1
	s_nop 0
	v_addc_co_u32_e32 v35, vcc, 0, v17, vcc
	v_add_co_u32_e32 v36, vcc, s2, v16
	s_mov_b32 s2, 0x18000
	s_nop 0
	v_addc_co_u32_e32 v37, vcc, 0, v17, vcc
	v_add_co_u32_e32 v38, vcc, s13, v16
	s_mov_b32 s13, 0xc000
	s_nop 0
	v_addc_co_u32_e32 v39, vcc, 0, v17, vcc
	v_add_co_u32_e32 v40, vcc, s13, v16
	s_mov_b32 s13, 0xe000
	s_nop 0
	v_addc_co_u32_e32 v41, vcc, 0, v17, vcc
	v_add_co_u32_e32 v42, vcc, s13, v16
	s_mov_b32 s13, 0x10000
	s_nop 0
	v_addc_co_u32_e32 v43, vcc, 0, v17, vcc
	global_load_dword v0, v[16:17], off nt
	global_load_dword v46, v[18:19], off nt
	global_load_dword v47, v[32:33], off nt
	global_load_dword v48, v[34:35], off nt
	global_load_dword v49, v[36:37], off nt
	global_load_dword v50, v[38:39], off nt
	global_load_dword v51, v[40:41], off nt
	global_load_dword v52, v[42:43], off nt
	v_add_co_u32_e32 v18, vcc, s13, v16
	s_mov_b32 s13, 0x12000
	s_nop 0
	v_addc_co_u32_e32 v19, vcc, 0, v17, vcc
	v_add_co_u32_e32 v32, vcc, s13, v16
	s_mov_b32 s13, 0x14000
	s_nop 0
	v_addc_co_u32_e32 v33, vcc, 0, v17, vcc
	v_add_co_u32_e32 v34, vcc, s13, v16
	s_mov_b32 s13, 0x16000
	s_nop 0
	v_addc_co_u32_e32 v35, vcc, 0, v17, vcc
	v_add_co_u32_e32 v36, vcc, s13, v16
	s_mov_b32 s13, 0x1a000
	s_nop 0
	v_addc_co_u32_e32 v37, vcc, 0, v17, vcc
	v_add_co_u32_e32 v38, vcc, s2, v16
	s_mov_b32 s2, 0x30000
	s_nop 0
	v_addc_co_u32_e32 v39, vcc, 0, v17, vcc
	v_add_co_u32_e32 v40, vcc, s13, v16
	s_mov_b32 s13, 0x1c000
	s_nop 0
	v_addc_co_u32_e32 v41, vcc, 0, v17, vcc
	v_add_co_u32_e32 v42, vcc, s13, v16
	s_mov_b32 s13, 0x1e000
	s_nop 0
	v_addc_co_u32_e32 v43, vcc, 0, v17, vcc
	v_add_co_u32_e32 v44, vcc, s13, v16
	s_mov_b32 s13, 0x20000
	s_nop 0
	v_addc_co_u32_e32 v45, vcc, 0, v17, vcc
	global_load_dword v53, v[18:19], off nt
	global_load_dword v54, v[32:33], off nt
	global_load_dword v55, v[34:35], off nt
	global_load_dword v56, v[36:37], off nt
	global_load_dword v57, v[38:39], off nt
	global_load_dword v58, v[40:41], off nt
	global_load_dword v59, v[42:43], off nt
	global_load_dword v60, v[44:45], off nt
	v_add_co_u32_e32 v18, vcc, s13, v16
	s_mov_b32 s13, 0x22000
	s_nop 0
	v_addc_co_u32_e32 v19, vcc, 0, v17, vcc
	v_add_co_u32_e32 v32, vcc, s13, v16
	s_mov_b32 s13, 0x24000
	s_nop 0
	v_addc_co_u32_e32 v33, vcc, 0, v17, vcc
	v_add_co_u32_e32 v34, vcc, s13, v16
	s_mov_b32 s13, 0x26000
	s_nop 0
	v_addc_co_u32_e32 v35, vcc, 0, v17, vcc
	v_add_co_u32_e32 v36, vcc, s13, v16
	s_mov_b32 s13, 0x28000
	s_nop 0
	v_addc_co_u32_e32 v37, vcc, 0, v17, vcc
	v_add_co_u32_e32 v38, vcc, s13, v16
	s_mov_b32 s13, 0x2a000
	s_nop 0
	v_addc_co_u32_e32 v39, vcc, 0, v17, vcc
	v_add_co_u32_e32 v40, vcc, s13, v16
	s_mov_b32 s13, 0x2c000
	s_nop 0
	v_addc_co_u32_e32 v41, vcc, 0, v17, vcc
	v_add_co_u32_e32 v42, vcc, s13, v16
	s_mov_b32 s13, 0x2e000
	s_nop 0
	v_addc_co_u32_e32 v43, vcc, 0, v17, vcc
	v_add_co_u32_e32 v44, vcc, s13, v16
	s_mov_b32 s13, 0x32000
	s_nop 0
	v_addc_co_u32_e32 v45, vcc, 0, v17, vcc
	global_load_dword v61, v[18:19], off nt
	global_load_dword v62, v[32:33], off nt
	global_load_dword v63, v[34:35], off nt
	global_load_dword v64, v[36:37], off nt
	global_load_dword v65, v[38:39], off nt
	global_load_dword v66, v[40:41], off nt
	global_load_dword v67, v[42:43], off nt
	s_nop 0
	global_load_dword v44, v[44:45], off nt
	v_add_co_u32_e32 v18, vcc, s2, v16
	s_add_u32 s12, s5, s12
	s_nop 0
	v_addc_co_u32_e32 v19, vcc, 0, v17, vcc
	v_add_co_u32_e32 v32, vcc, s13, v16
	s_mov_b32 s13, 0x34000
	s_nop 0
	v_addc_co_u32_e32 v33, vcc, 0, v17, vcc
	v_add_co_u32_e32 v34, vcc, s13, v16
	s_mov_b32 s13, 0x36000
	s_nop 0
	v_addc_co_u32_e32 v35, vcc, 0, v17, vcc
	v_add_co_u32_e32 v36, vcc, s13, v16
	s_mov_b32 s13, 0x38000
	s_nop 0
	v_addc_co_u32_e32 v37, vcc, 0, v17, vcc
	v_add_co_u32_e32 v38, vcc, s13, v16
	s_mov_b32 s13, 0x3a000
	s_nop 0
	v_addc_co_u32_e32 v39, vcc, 0, v17, vcc
	v_add_co_u32_e32 v40, vcc, s13, v16
	s_mov_b32 s13, 0x3c000
	s_nop 0
	v_addc_co_u32_e32 v41, vcc, 0, v17, vcc
	v_add_co_u32_e32 v42, vcc, s13, v16
	s_mov_b32 s13, 0x3e000
	s_nop 0
	v_addc_co_u32_e32 v43, vcc, 0, v17, vcc
	v_add_co_u32_e32 v16, vcc, s13, v16
	s_addc_u32 s13, s11, 0
	s_nop 0
	v_addc_co_u32_e32 v17, vcc, 0, v17, vcc
	global_load_dword v18, v[18:19], off nt
	s_nop 0
	global_load_dword v19, v[32:33], off nt
	s_nop 0
	global_load_dword v32, v[34:35], off nt
	global_load_dword v33, v[36:37], off nt
	s_nop 0
	global_load_dword v34, v[38:39], off nt
	global_load_dword v35, v[40:41], off nt
	global_load_dword v36, v[42:43], off nt
	s_nop 0
	global_load_dword v16, v[16:17], off nt
	s_waitcnt vmcnt(30)
; #define LAS __attribute__((address_space(3)))
; __device__ __forceinline__ unsigned pk2(float lo, float hi) { return pg8::cvt_pk_bf16(lo, hi); }
; #define LDS_WAIT() asm volatile("s_waitcnt lgkmcnt(0)" ::: "memory")
; __device__ __forceinline__ void tr_item(const float* W, int K, int N, bf16_t* WT, int rowbase, int k0, int n0, LAS float* scr, int lane) {
;     ...
;     for (int i = 0; i < 32; ++i) { const int kk = 2 * i + (lane >> 5); scr[kk * 33 + (lane & 31)] = tv[i]; }
;     LDS_WAIT();
;     const int c = lane & 7;
; #pragma unroll
;     for (int j = 0; j < 4; ++j) {
;         const int nn = (lane >> 3) + 8 * j; const LAS float* s = scr + (8 * c) * 33 + nn;
;         u32x4 o; o.x = pk2(s[0 * 33], s[1 * 33]); o.y = pk2(s[2 * 33], s[3 * 33]); o.z = pk2(s[4 * 33], s[5 * 33]); o.w = pk2(s[6 * 33], s[7 * 33]);
;         *(u32x4*)(WT + (size_t)(rowbase + nn) * K + k0 + 8 * c) = o;
;     }
;     LDS_WAIT();
	ds_write2_b32 v7, v0, v46 offset1:66
	s_waitcnt vmcnt(28)
	ds_write2_b32 v7, v47, v48 offset0:132 offset1:198
	s_waitcnt vmcnt(26)
	ds_write2_b32 v25, v49, v50 offset0:8 offset1:74
	s_waitcnt vmcnt(24)
	ds_write2_b32 v25, v51, v52 offset0:140 offset1:206
	s_waitcnt vmcnt(22)
	ds_write2_b32 v26, v53, v54 offset0:16 offset1:82
	s_waitcnt vmcnt(20)
	ds_write2_b32 v26, v55, v56 offset0:148 offset1:214
	s_waitcnt vmcnt(18)
	ds_write2_b32 v27, v57, v58 offset0:24 offset1:90
	s_waitcnt vmcnt(16)
	ds_write2_b32 v27, v59, v60 offset0:156 offset1:222
	s_waitcnt vmcnt(14)
	ds_write2_b32 v28, v61, v62 offset0:32 offset1:98
	s_waitcnt vmcnt(12)
	ds_write2_b32 v28, v63, v64 offset0:164 offset1:230
	s_waitcnt vmcnt(10)
	ds_write2_b32 v29, v65, v66 offset0:40 offset1:106
	s_waitcnt vmcnt(8)
	ds_write2_b32 v29, v67, v44 offset0:172 offset1:238
	s_waitcnt vmcnt(6)
	ds_write2_b32 v30, v18, v19 offset0:48 offset1:114
	s_waitcnt vmcnt(4)
	ds_write2_b32 v30, v32, v33 offset0:180 offset1:246
	s_waitcnt vmcnt(2)
	ds_write2_b32 v31, v34, v35 offset0:56 offset1:122
	s_waitcnt vmcnt(0)
	ds_write2_b32 v31, v36, v16 offset0:188 offset1:254
	s_waitcnt lgkmcnt(0)
	v_lshlrev_b32_e32 v0, 1, v6
	ds_read2_b32 v[80:81], v21 offset1:33
	ds_read2_b32 v[82:83], v21 offset0:66 offset1:99
	ds_read2_b32 v[84:85], v21 offset0:132 offset1:165
	ds_read2_b32 v[86:87], v21 offset0:198 offset1:231
	ds_read2_b32 v[88:89], v21 offset0:8 offset1:41
	ds_read2_b32 v[90:91], v21 offset0:74 offset1:107
	ds_read2_b32 v[92:93], v21 offset0:140 offset1:173
	ds_read2_b32 v[94:95], v21 offset0:206 offset1:239
	ds_read2_b32 v[96:97], v21 offset0:16 offset1:49
	ds_read2_b32 v[98:99], v21 offset0:82 offset1:115
	ds_read2_b32 v[100:101], v21 offset0:148 offset1:181
	ds_read2_b32 v[102:103], v21 offset0:214 offset1:247
	ds_read2_b32 v[104:105], v21 offset0:24 offset1:57
	ds_read2_b32 v[106:107], v21 offset0:90 offset1:123
	ds_read2_b32 v[108:109], v21 offset0:156 offset1:189
	v_lshl_add_u64 v[34:35], s[12:13], 0, v[0:1]
	v_or_b32_e32 v0, s4, v20
	s_waitcnt lgkmcnt(14)
	ds_read2_b32 v[110:111], v21 offset0:222 offset1:255
	v_cvt_pk_bf16_f32 v16, v80, v81
	v_mul_u32_u24_e32 v0, 0xb00, v0
	s_waitcnt lgkmcnt(14)
	v_cvt_pk_bf16_f32 v17, v82, v83
	v_lshlrev_b32_e32 v0, 1, v0
	s_waitcnt lgkmcnt(13)
	v_cvt_pk_bf16_f32 v18, v84, v85
	s_waitcnt lgkmcnt(12)
	v_cvt_pk_bf16_f32 v19, v86, v87
	v_lshl_add_u64 v[36:37], v[34:35], 0, v[0:1]
	v_or_b32_e32 v0, s4, v22
	global_store_dwordx4 v[36:37], v[16:19], off
	v_mul_u32_u24_e32 v0, 0xb00, v0
	v_lshlrev_b32_e32 v0, 1, v0
	s_waitcnt lgkmcnt(11)
	v_cvt_pk_bf16_f32 v16, v88, v89
	s_waitcnt lgkmcnt(10)
	v_cvt_pk_bf16_f32 v17, v90, v91
	s_waitcnt lgkmcnt(9)
	v_cvt_pk_bf16_f32 v18, v92, v93
	s_waitcnt lgkmcnt(8)
	v_cvt_pk_bf16_f32 v19, v94, v95
	v_lshl_add_u64 v[36:37], v[34:35], 0, v[0:1]
	v_or_b32_e32 v0, s4, v23
	global_store_dwordx4 v[36:37], v[16:19], off
	v_mul_u32_u24_e32 v0, 0xb00, v0
	v_lshlrev_b32_e32 v0, 1, v0
	s_waitcnt lgkmcnt(7)
	v_cvt_pk_bf16_f32 v16, v96, v97
	s_waitcnt lgkmcnt(6)
	v_cvt_pk_bf16_f32 v17, v98, v99
	s_waitcnt lgkmcnt(5)
	v_cvt_pk_bf16_f32 v18, v100, v101
	s_waitcnt lgkmcnt(4)
	v_cvt_pk_bf16_f32 v19, v102, v103
	v_lshl_add_u64 v[36:37], v[34:35], 0, v[0:1]
	global_store_dwordx4 v[36:37], v[16:19], off
	v_or_b32_e32 v0, s4, v24
	v_mul_u32_u24_e32 v0, 0xb00, v0
	s_waitcnt lgkmcnt(3)
	v_cvt_pk_bf16_f32 v16, v104, v105
	s_waitcnt lgkmcnt(2)
	v_cvt_pk_bf16_f32 v17, v106, v107
	s_waitcnt lgkmcnt(1)
	v_cvt_pk_bf16_f32 v18, v108, v109
	v_lshlrev_b32_e32 v0, 1, v0
	s_waitcnt lgkmcnt(0)
	v_cvt_pk_bf16_f32 v19, v110, v111
	v_lshl_add_u64 v[32:33], v[34:35], 0, v[0:1]
	global_store_dwordx4 v[32:33], v[16:19], off
	s_waitcnt lgkmcnt(0)

; #define LAS __attribute__((address_space(3)))
;     __device__ __forceinline__ const float* in(int i) const { return (const float*)(const __attribute__((address_space(1))) float*)ld(i); }
;     __device__ __forceinline__ unsigned char* ws() const { return (unsigned char*)(__attribute__((address_space(1))) unsigned char*)ld(35); }
; __device__ __forceinline__ void tr_item(const float* W, int K, int N, bf16_t* WT, int rowbase, int k0, int n0, LAS float* scr, int lane) {
;     const int n = n0 + (lane & 31);
;     float tv[32];
; #pragma unroll
;     for (int i = 0; i < 32; ++i) { const int kk = 2 * i + (lane >> 5); tv[i] = 0.f; if (n < N) tv[i] = __builtin_nontemporal_load(W + (size_t)(k0 + kk) * N + n); }
; __device__ __forceinline__ void phase_convert(const Params& p, int l, LAS unsigned char* lds, int gw, int ngw, int wave, int lane) {
;     ...
;         if (r < 4 * I_UP) {
;             const int which = r / I_UP; r -= which * I_UP;
;             const int src = (which == 0) ? 2 : (which == 1) ? 3 : (which == 2) ? 30 : 31;
;             bf16_t* dst = (bf16_t*)(ws + ((which < 2) ? WS_WUP1 : WS_WUP2));
;             const int kb = r / 88, nb = r % 88, n0 = 32 * nb;
;             const int rowbase = 256 * (n0 / 128) + (n0 % 128) + ((which & 1) ? 128 : 0);
;             tr_item(p.in(src) + (size_t)l * D * FF, D, FF, dst, rowbase, 64 * kb, n0, scr, lane);
.LBB0_134:
	s_andn2_b64 vcc, exec, s[4:5]
	s_cbranch_vccnz .LBB0_15
	s_mul_hi_i32 s4, s19, 0x2e8ba2e9
	s_lshr_b32 s5, s4, 31
	s_ashr_i32 s4, s4, 8
	s_add_i32 s4, s4, s5
	s_mul_i32 s5, s4, 0xfffffa80
	s_add_i32 s5, s19, s5
	s_add_i32 s11, s19, 0x57f
	s_add_i32 s12, s19, 0xfffffa80
	s_add_i32 s13, s19, 0xfffff500
	s_cmpk_lt_u32 s13, 0x580
	s_movk_i32 s13, 0xf0
	s_cselect_b32 s13, s13, 0xf8
	s_cmpk_gt_u32 s12, 0x57f
	s_cselect_b32 s12, s13, 24
	s_cmpk_gt_u32 s11, 0xafe
	s_cselect_b32 s11, s12, 16
	s_cmpk_lt_i32 s19, 0xb00
	s_cselect_b32 s12, s25, 0x5080000
	s_add_u32 s12, s0, s12
	s_mul_hi_i32 s20, s5, 0x2e8ba2e9
	s_addc_u32 s13, s1, 0
	s_lshr_b32 s21, s20, 31
	s_ashr_i32 s20, s20, 4
	s_add_i32 s22, s20, s21
	s_mul_i32 s20, s22, 0x58
	s_sub_i32 s5, s5, s20
	s_bfe_i32 s20, s5, 0x80000
	s_add_i32 s11, s11, 0
	s_bfe_u32 s20, s20, 0x2000d
	s_add_i32 s11, s11, 0x23800
	s_lshl_b32 s23, s5, 5
	s_add_i32 s20, s5, s20
	s_bfe_u32 s5, s5, 0x70013
	v_mov_b32_e32 v0, s11
	s_add_i32 s5, s23, s5
	ds_read_b64 v[16:17], v0
	s_bfe_i32 s20, s20, 0x80000
	s_and_b32 s5, s5, 0xff80
	s_sext_i32_i16 s20, s20
	s_sub_i32 s5, s23, s5
	s_lshl_b32 s4, s4, 7
	s_lshl_b32 s20, s20, 6
	s_sext_i32_i16 s5, s5
	s_and_b32 s4, s4, 0x80
	s_and_b32 s20, s20, 0xffffff00
	s_add_i32 s11, s4, s5
	s_add_i32 s11, s11, s20
	s_waitcnt lgkmcnt(0)
	v_readfirstlane_b32 s4, v16
	v_readfirstlane_b32 s5, v17
	s_add_u32 s20, s4, s15
	s_addc_u32 s21, s5, 0
	s_lshl_b32 s4, s22, 6
	v_or_b32_e32 v16, s23, v2
	v_or_b32_e32 v0, s4, v3
	v_ashrrev_i32_e32 v17, 31, v16
	v_lshl_add_u64 v[16:17], v[16:17], 2, s[20:21]
	v_or_b32_e32 v32, 2, v0
	v_or_b32_e32 v34, 4, v0
	v_or_b32_e32 v36, 6, v0
	v_or_b32_e32 v38, 8, v0
	v_or_b32_e32 v40, 10, v0
	v_or_b32_e32 v42, 12, v0
	v_or_b32_e32 v44, 14, v0
	v_mad_i64_i32 v[18:19], s[20:21], v0, s55, v[16:17]
	v_mad_i64_i32 v[32:33], s[20:21], v32, s55, v[16:17]
	v_mad_i64_i32 v[34:35], s[20:21], v34, s55, v[16:17]
	v_mad_i64_i32 v[36:37], s[20:21], v36, s55, v[16:17]
	v_mad_i64_i32 v[38:39], s[20:21], v38, s55, v[16:17]
	v_mad_i64_i32 v[40:41], s[20:21], v40, s55, v[16:17]
	v_mad_i64_i32 v[42:43], s[20:21], v42, s55, v[16:17]
	v_mad_i64_i32 v[44:45], s[20:21], v44, s55, v[16:17]
	global_load_dword v46, v[18:19], off nt
	global_load_dword v47, v[32:33], off nt
	global_load_dword v48, v[34:35], off nt
	global_load_dword v49, v[36:37], off nt
	global_load_dword v50, v[38:39], off nt
	global_load_dword v51, v[40:41], off nt
	global_load_dword v52, v[42:43], off nt
	global_load_dword v53, v[44:45], off nt
	v_or_b32_e32 v18, 16, v0
	v_or_b32_e32 v32, 18, v0
	v_or_b32_e32 v34, 20, v0
	v_or_b32_e32 v36, 22, v0
	v_or_b32_e32 v38, 24, v0
	v_or_b32_e32 v40, 26, v0
	v_or_b32_e32 v42, 28, v0
	v_or_b32_e32 v44, 30, v0
	v_mad_i64_i32 v[18:19], s[20:21], v18, s55, v[16:17]
	v_mad_i64_i32 v[32:33], s[20:21], v32, s55, v[16:17]
	v_mad_i64_i32 v[34:35], s[20:21], v34, s55, v[16:17]
	v_mad_i64_i32 v[36:37], s[20:21], v36, s55, v[16:17]
	v_mad_i64_i32 v[38:39], s[20:21], v38, s55, v[16:17]
	v_mad_i64_i32 v[40:41], s[20:21], v40, s55, v[16:17]
	v_mad_i64_i32 v[42:43], s[20:21], v42, s55, v[16:17]
	v_mad_i64_i32 v[44:45], s[20:21], v44, s55, v[16:17]
	global_load_dword v54, v[18:19], off nt
	global_load_dword v55, v[32:33], off nt
	global_load_dword v56, v[34:35], off nt
	global_load_dword v57, v[36:37], off nt
	global_load_dword v58, v[38:39], off nt
	global_load_dword v59, v[40:41], off nt
	global_load_dword v60, v[42:43], off nt
	global_load_dword v61, v[44:45], off nt
	v_or_b32_e32 v18, 32, v0
	v_or_b32_e32 v32, 34, v0
	v_or_b32_e32 v34, 36, v0
	v_or_b32_e32 v36, 38, v0
	v_or_b32_e32 v38, 40, v0
	v_or_b32_e32 v40, 42, v0
	v_or_b32_e32 v42, 44, v0
	v_or_b32_e32 v44, 46, v0
	v_mad_i64_i32 v[18:19], s[20:21], v18, s55, v[16:17]
	v_mad_i64_i32 v[32:33], s[20:21], v32, s55, v[16:17]
	v_mad_i64_i32 v[34:35], s[20:21], v34, s55, v[16:17]
	v_mad_i64_i32 v[36:37], s[20:21], v36, s55, v[16:17]
	v_mad_i64_i32 v[38:39], s[20:21], v38, s55, v[16:17]
	v_mad_i64_i32 v[40:41], s[20:21], v40, s55, v[16:17]
	v_mad_i64_i32 v[42:43], s[20:21], v42, s55, v[16:17]
	v_mad_i64_i32 v[44:45], s[20:21], v44, s55, v[16:17]
	global_load_dword v62, v[18:19], off nt
	global_load_dword v63, v[32:33], off nt
	global_load_dword v64, v[34:35], off nt
	global_load_dword v65, v[36:37], off nt
	global_load_dword v66, v[38:39], off nt
	global_load_dword v67, v[40:41], off nt
	global_load_dword v68, v[42:43], off nt
	s_nop 0
	global_load_dword v44, v[44:45], off nt
	v_or_b32_e32 v18, 48, v0
	v_or_b32_e32 v32, 50, v0
	v_or_b32_e32 v34, 52, v0
	v_or_b32_e32 v36, 54, v0
	v_or_b32_e32 v38, 56, v0
	v_or_b32_e32 v40, 58, v0
	v_or_b32_e32 v42, 60, v0
	v_or_b32_e32 v0, 62, v0
	v_mad_i64_i32 v[18:19], s[20:21], v18, s55, v[16:17]
	v_mad_i64_i32 v[32:33], s[20:21], v32, s55, v[16:17]
	v_mad_i64_i32 v[34:35], s[20:21], v34, s55, v[16:17]
	v_mad_i64_i32 v[36:37], s[20:21], v36, s55, v[16:17]
	v_mad_i64_i32 v[38:39], s[20:21], v38, s55, v[16:17]
	v_mad_i64_i32 v[40:41], s[20:21], v40, s55, v[16:17]
	v_mad_i64_i32 v[42:43], s[20:21], v42, s55, v[16:17]
	v_mad_i64_i32 v[16:17], s[20:21], v0, s55, v[16:17]
	global_load_dword v0, v[18:19], off nt
	s_nop 0
	global_load_dword v18, v[32:33], off nt
	global_load_dword v19, v[34:35], off nt
	s_nop 0
	global_load_dword v32, v[36:37], off nt
	global_load_dword v33, v[38:39], off nt
	global_load_dword v34, v[40:41], off nt
	global_load_dword v35, v[42:43], off nt
	s_nop 0
	global_load_dword v16, v[16:17], off nt
	s_waitcnt vmcnt(30)
; #define LAS __attribute__((address_space(3)))
; __device__ __forceinline__ unsigned pk2(float lo, float hi) { return pg8::cvt_pk_bf16(lo, hi); }
; #define LDS_WAIT() asm volatile("s_waitcnt lgkmcnt(0)" ::: "memory")
; __device__ __forceinline__ void tr_item(const float* W, int K, int N, bf16_t* WT, int rowbase, int k0, int n0, LAS float* scr, int lane) {
;     ...
;     for (int i = 0; i < 32; ++i) { const int kk = 2 * i + (lane >> 5); scr[kk * 33 + (lane & 31)] = tv[i]; }
;     LDS_WAIT();
;     const int c = lane & 7;
; #pragma unroll
;     for (int j = 0; j < 4; ++j) {
;         const int nn = (lane >> 3) + 8 * j; const LAS float* s = scr + (8 * c) * 33 + nn;
;         u32x4 o; o.x = pk2(s[0 * 33], s[1 * 33]); o.y = pk2(s[2 * 33], s[3 * 33]); o.z = pk2(s[4 * 33], s[5 * 33]); o.w = pk2(s[6 * 33], s[7 * 33]);
;         *(u32x4*)(WT + (size_t)(rowbase + nn) * K + k0 + 8 * c) = o;
;     }
;     LDS_WAIT();
	ds_write2_b32 v7, v46, v47 offset1:66
	s_waitcnt vmcnt(28)
	ds_write2_b32 v7, v48, v49 offset0:132 offset1:198
	s_waitcnt vmcnt(26)
	ds_write2_b32 v25, v50, v51 offset0:8 offset1:74
	s_waitcnt vmcnt(24)
	ds_write2_b32 v25, v52, v53 offset0:140 offset1:206
	s_waitcnt vmcnt(22)
	ds_write2_b32 v26, v54, v55 offset0:16 offset1:82
	s_waitcnt vmcnt(20)
	ds_write2_b32 v26, v56, v57 offset0:148 offset1:214
	s_waitcnt vmcnt(18)
	ds_write2_b32 v27, v58, v59 offset0:24 offset1:90
	s_waitcnt vmcnt(16)
	ds_write2_b32 v27, v60, v61 offset0:156 offset1:222
	s_waitcnt vmcnt(14)
	ds_write2_b32 v28, v62, v63 offset0:32 offset1:98
	s_waitcnt vmcnt(12)
	ds_write2_b32 v28, v64, v65 offset0:164 offset1:230
	s_waitcnt vmcnt(10)
	ds_write2_b32 v29, v66, v67 offset0:40 offset1:106
	s_waitcnt vmcnt(8)
	ds_write2_b32 v29, v68, v44 offset0:172 offset1:238
	s_waitcnt vmcnt(6)
	ds_write2_b32 v30, v0, v18 offset0:48 offset1:114
	s_waitcnt vmcnt(4)
	ds_write2_b32 v30, v19, v32 offset0:180 offset1:246
	s_waitcnt vmcnt(2)
	ds_write2_b32 v31, v33, v34 offset0:56 offset1:122
	s_waitcnt vmcnt(0)
	ds_write2_b32 v31, v35, v16 offset0:188 offset1:254
	s_waitcnt lgkmcnt(0)
	ds_read2_b32 v[80:81], v21 offset1:33
	ds_read2_b32 v[82:83], v21 offset0:66 offset1:99
	ds_read2_b32 v[84:85], v21 offset0:132 offset1:165
	ds_read2_b32 v[86:87], v21 offset0:198 offset1:231
	ds_read2_b32 v[88:89], v21 offset0:8 offset1:41
	ds_read2_b32 v[90:91], v21 offset0:74 offset1:107
	ds_read2_b32 v[92:93], v21 offset0:140 offset1:173
	ds_read2_b32 v[94:95], v21 offset0:206 offset1:239
	ds_read2_b32 v[96:97], v21 offset0:16 offset1:49
	ds_read2_b32 v[98:99], v21 offset0:82 offset1:115
	ds_read2_b32 v[100:101], v21 offset0:148 offset1:181
	ds_read2_b32 v[102:103], v21 offset0:214 offset1:247
	ds_read2_b32 v[104:105], v21 offset0:24 offset1:57
	ds_read2_b32 v[106:107], v21 offset0:90 offset1:123
	ds_read2_b32 v[108:109], v21 offset0:156 offset1:189
	s_waitcnt lgkmcnt(14)
	ds_read2_b32 v[110:111], v21 offset0:222 offset1:255
	v_cvt_pk_bf16_f32 v16, v80, v81
	s_waitcnt lgkmcnt(14)
	v_cvt_pk_bf16_f32 v17, v82, v83
	s_ashr_i32 s5, s4, 31
	s_lshl_b64 s[4:5], s[4:5], 1
	s_waitcnt lgkmcnt(13)
	v_cvt_pk_bf16_f32 v18, v84, v85
	s_add_u32 s4, s12, s4
	s_waitcnt lgkmcnt(12)
	v_cvt_pk_bf16_f32 v19, v86, v87
	v_or_b32_e32 v32, s11, v20
	s_addc_u32 s5, s13, s5
	v_lshlrev_b32_e32 v0, 1, v6
	v_ashrrev_i32_e32 v33, 31, v32
	v_lshl_add_u64 v[34:35], s[4:5], 0, v[0:1]
	v_lshlrev_b64 v[32:33], 11, v[32:33]
	v_lshl_add_u64 v[32:33], v[34:35], 0, v[32:33]
	global_store_dwordx4 v[32:33], v[16:19], off
	s_nop 0
	s_waitcnt lgkmcnt(11)
	v_cvt_pk_bf16_f32 v16, v88, v89
	s_waitcnt lgkmcnt(10)
	v_cvt_pk_bf16_f32 v17, v90, v91
	s_waitcnt lgkmcnt(9)
	v_cvt_pk_bf16_f32 v18, v92, v93
	s_waitcnt lgkmcnt(8)
	v_cvt_pk_bf16_f32 v19, v94, v95
	v_or_b32_e32 v32, s11, v22
	v_ashrrev_i32_e32 v33, 31, v32
	v_lshlrev_b64 v[32:33], 11, v[32:33]
	v_lshl_add_u64 v[32:33], v[34:35], 0, v[32:33]
	global_store_dwordx4 v[32:33], v[16:19], off
	s_nop 0
	s_waitcnt lgkmcnt(7)
	v_cvt_pk_bf16_f32 v16, v96, v97
	s_waitcnt lgkmcnt(6)
	v_cvt_pk_bf16_f32 v17, v98, v99
	s_waitcnt lgkmcnt(5)
	v_cvt_pk_bf16_f32 v18, v100, v101
	s_waitcnt lgkmcnt(4)
	v_cvt_pk_bf16_f32 v19, v102, v103
	v_or_b32_e32 v32, s11, v23
	v_ashrrev_i32_e32 v33, 31, v32
	v_lshlrev_b64 v[32:33], 11, v[32:33]
	v_lshl_add_u64 v[32:33], v[34:35], 0, v[32:33]
	global_store_dwordx4 v[32:33], v[16:19], off
	s_nop 0
	s_waitcnt lgkmcnt(3)
	v_cvt_pk_bf16_f32 v16, v104, v105
	s_waitcnt lgkmcnt(2)
	v_cvt_pk_bf16_f32 v17, v106, v107
	s_waitcnt lgkmcnt(1)
	v_cvt_pk_bf16_f32 v18, v108, v109
	s_waitcnt lgkmcnt(0)
	v_cvt_pk_bf16_f32 v19, v110, v111
	v_or_b32_e32 v32, s11, v24
	v_ashrrev_i32_e32 v33, 31, v32
	v_lshlrev_b64 v[32:33], 11, v[32:33]
	v_lshl_add_u64 v[32:33], v[34:35], 0, v[32:33]
	global_store_dwordx4 v[32:33], v[16:19], off
	s_waitcnt lgkmcnt(0)
	s_branch .LBB0_15
